# XCC id published into the group mask at kernel start instead of before the first grid barrier
# baseline (speedup 1.0000x reference)
; #define LAS __attribute__((address_space(3)))
; __device__ __forceinline__ unsigned xb_add(unsigned* p, unsigned v) { return __hip_atomic_fetch_add(p, v, __ATOMIC_RELAXED, __HIP_MEMORY_SCOPE_AGENT); }
; __device__ __forceinline__ unsigned xb_xcc_id() { return (unsigned)__builtin_amdgcn_s_getreg((3 << 11) | 20) & 0xFu; }
; __global__ void __launch_bounds__(NWAVES * 64, 2) fwd_kernel(Args args) {
;     extern __shared__ __attribute__((aligned(16))) unsigned char lds_raw[];
;     LAS unsigned char* lds = (LAS unsigned char*)lds_raw;
;     unsigned char* ws = args.ws;
;     const int lo = args.ph_lo, hi = args.ph_hi;
;     const int G = gridDim.x;
;     ...
;     unsigned* barw = (unsigned*)ws;
;     volatile LAS unsigned* bst = (volatile LAS unsigned*)(lds + LDS_BYTES - 64);
;     if (threadIdx.x == 0) { bst[0] = 0u; bst[1] = 0u; (void)xb_add(barw + 64 * xb_xcc_id(), 1u); }
_Z10fwd_kernel4Args:
	s_mov_b32 s70, s2
	s_load_dwordx4 s[12:15], s[0:1], 0x80
	s_load_dwordx2 s[2:3], s[0:1], 0x90
	s_load_dword s88, s[0:1], 0x98
	s_add_u32 s90, s0, 0x98
	s_addc_u32 s91, s1, 0
	v_and_b32_e32 v184, 0x3ff, v0
	s_waitcnt lgkmcnt(0)
	v_writelane_b32 v254, s2, 0
	v_cmp_eq_u32_e64 s[4:5], 0, v184
	s_nop 0
	v_writelane_b32 v254, s3, 1
	s_mov_b64 s[2:3], exec
	v_writelane_b32 v254, s4, 2
	s_nop 1
	v_writelane_b32 v254, s5, 3
	s_and_b64 s[4:5], s[2:3], s[4:5]
	s_mov_b64 exec, s[4:5]
	s_cbranch_execz .LBB0_3
	s_add_i32 s6, 0, 0x23fc0
	v_mov_b32_e32 v1, 0
	v_mov_b32_e32 v2, s6
	s_add_i32 s6, 0, 0x23fc4
	s_mov_b64 s[4:5], exec
	ds_write_b32 v2, v1
	v_mov_b32_e32 v2, s6
	ds_write_b32 v2, v1
	v_mbcnt_lo_u32_b32 v1, s4, 0
	v_mbcnt_hi_u32_b32 v1, s5, v1
	v_cmp_eq_u32_e32 vcc, 0, v1
	s_getreg_b32 s6, hwreg(HW_REG_XCC_ID, 0, 4)
	s_and_b64 s[8:9], exec, vcc
	s_mov_b64 exec, s[8:9]
	s_cbranch_execz .LBB0_3
	s_lshl_b32 s6, s6, 8
	s_and_b32 s6, s6, 0xf00
	s_bcnt1_i32_b64 s4, s[4:5]
	v_mov_b32_e32 v1, s6
	v_mov_b32_e32 v2, s4
	global_atomic_add v1, v2, s[14:15]
	s_getreg_b32 s6, hwreg(HW_REG_XCC_ID, 0, 4)
	s_lshl_b32 s6, 1, s6
	s_and_b32 s4, s70, 7
	s_lshl_b32 s4, s4, 8
	s_add_i32 s4, s4, 0x12440
	v_mov_b32_e32 v1, s4
	v_mov_b32_e32 v2, s6
	global_atomic_or v1, v2, s[14:15]
